# v_rm_m1 + X4 epilogue residual tile read via coalesced LDS-DMA + ds_read (was 16 uncoalesced global loads)
# speedup vs baseline: 1.0033x; 1.0033x over previous
.LBB0_874:
	v_lshl_or_b32 v196, s60, 8, v226
	v_lshl_add_u32 v194, s61, 8, v5
	s_barrier
	v_readfirstlane_b32 s30, v0
	v_and_b32_e32 v151, 63, v0
	v_lshrrev_b32_e32 v152, 3, v151
	v_and_b32_e32 v150, -16, v194
	v_add_u32_e32 v150, v150, v152
	v_lshlrev_b32_e32 v150, 11, v150
	v_and_b32_e32 v153, 7, v151
	v_xor_b32_e32 v153, v153, v152
	v_lshl_add_u32 v150, v153, 4, v150
	v_lshrrev_b32_e32 v153, 5, v196
	v_lshl_add_u32 v150, v153, 6, v150
	s_lshr_b32 s30, s30, 6
	s_lshl_b32 s30, s30, 14
	v_and_b32_e32 v153, 7, v151
	v_lshrrev_b32_e32 v152, 4, v151
	v_xor_b32_e32 v152, v152, v153
	v_lshlrev_b32_e32 v152, 4, v152
	v_lshl_add_u32 v152, v153, 7, v152
	v_bfe_u32 v153, v151, 3, 1
	v_lshl_add_u32 v152, v153, 10, v152
	v_add_u32_e32 v151, s30, v152
	v_xor_b32_e32 v152, 64, v151
	v_ashrrev_i32_e32 v197, 31, v196
	v_lshlrev_b64 v[222:223], 1, v[196:197]
	v_ashrrev_i32_e32 v195, 31, v194
	v_lshl_add_u64 v[126:127], s[4:5], 0, v[222:223]
	v_lshlrev_b64 v[224:225], 11, v[194:195]
	v_lshl_add_u64 v[128:129], v[126:127], 0, v[224:225]
	s_add_i32 m0, s30, 0x0
	s_add_u32 s34, s4, 0x0
	s_addc_u32 s35, s5, 0
	global_load_lds_dwordx4 v150, s[34:35]
	s_add_i32 m0, s30, 0x400
	s_add_u32 s34, s4, 0x4000
	s_addc_u32 s35, s5, 0
	global_load_lds_dwordx4 v150, s[34:35]
	v_or_b32_e32 v128, 16, v194
	v_ashrrev_i32_e32 v129, 31, v128
	v_lshlrev_b64 v[220:221], 11, v[128:129]
	v_lshl_add_u64 v[128:129], v[126:127], 0, v[220:221]
	s_add_i32 m0, s30, 0x800
	s_add_u32 s34, s4, 0x8000
	s_addc_u32 s35, s5, 0
	global_load_lds_dwordx4 v150, s[34:35]
	s_add_i32 m0, s30, 0xc00
	s_add_u32 s34, s4, 0xc000
	s_addc_u32 s35, s5, 0
	global_load_lds_dwordx4 v150, s[34:35]
	v_or_b32_e32 v128, 32, v194
	v_ashrrev_i32_e32 v129, 31, v128
	v_lshlrev_b64 v[218:219], 11, v[128:129]
	v_lshl_add_u64 v[128:129], v[126:127], 0, v[218:219]
	s_add_i32 m0, s30, 0x1000
	s_add_u32 s34, s4, 0x10000
	s_addc_u32 s35, s5, 0
	global_load_lds_dwordx4 v150, s[34:35]
	s_add_i32 m0, s30, 0x1400
	s_add_u32 s34, s4, 0x14000
	s_addc_u32 s35, s5, 0
	global_load_lds_dwordx4 v150, s[34:35]
	v_or_b32_e32 v128, 48, v194
	v_ashrrev_i32_e32 v129, 31, v128
	s_mov_b64 s[22:23], 0x40000
	v_lshlrev_b64 v[216:217], 11, v[128:129]
	v_lshl_add_u64 v[214:215], v[224:225], 0, s[22:23]
	s_mov_b64 s[22:23], 0x48000
	v_lshl_add_u64 v[128:129], v[126:127], 0, v[216:217]
	v_lshl_add_u64 v[212:213], v[224:225], 0, s[22:23]
	s_mov_b64 s[22:23], 0x50000
	s_add_i32 m0, s30, 0x1800
	s_add_u32 s34, s4, 0x18000
	s_addc_u32 s35, s5, 0
	global_load_lds_dwordx4 v150, s[34:35]
	s_add_i32 m0, s30, 0x1c00
	s_add_u32 s34, s4, 0x1c000
	s_addc_u32 s35, s5, 0
	global_load_lds_dwordx4 v150, s[34:35]
	v_lshl_add_u64 v[128:129], v[126:127], 0, v[214:215]
	v_lshl_add_u64 v[200:201], v[224:225], 0, s[22:23]
	s_mov_b64 s[22:23], 0x58000
	s_add_i32 m0, s30, 0x2000
	s_add_u32 s34, s4, 0x40000
	s_addc_u32 s35, s5, 0
	global_load_lds_dwordx4 v150, s[34:35]
	s_add_i32 m0, s30, 0x2400
	s_add_u32 s34, s4, 0x44000
	s_addc_u32 s35, s5, 0
	global_load_lds_dwordx4 v150, s[34:35]
	v_lshl_add_u64 v[128:129], v[126:127], 0, v[212:213]
	v_lshl_add_u64 v[198:199], v[224:225], 0, s[22:23]
	s_add_i32 m0, s30, 0x2800
	s_add_u32 s34, s4, 0x48000
	s_addc_u32 s35, s5, 0
	global_load_lds_dwordx4 v150, s[34:35]
	s_add_i32 m0, s30, 0x2c00
	s_add_u32 s34, s4, 0x4c000
	s_addc_u32 s35, s5, 0
	global_load_lds_dwordx4 v150, s[34:35]
	v_lshl_add_u64 v[128:129], v[126:127], 0, v[200:201]
	v_lshl_add_u64 v[126:127], v[126:127], 0, v[198:199]
	s_add_i32 m0, s30, 0x3000
	s_add_u32 s34, s4, 0x50000
	s_addc_u32 s35, s5, 0
	global_load_lds_dwordx4 v150, s[34:35]
	s_add_i32 m0, s30, 0x3400
	s_add_u32 s34, s4, 0x54000
	s_addc_u32 s35, s5, 0
	global_load_lds_dwordx4 v150, s[34:35]
	s_add_i32 m0, s30, 0x3800
	s_add_u32 s34, s4, 0x58000
	s_addc_u32 s35, s5, 0
	global_load_lds_dwordx4 v150, s[34:35]
	s_nop 0
	s_add_i32 m0, s30, 0x3c00
	s_add_u32 s34, s4, 0x5c000
	s_addc_u32 s35, s5, 0
	global_load_lds_dwordx4 v150, s[34:35]
	s_lshl_b32 s13, s60, 2
	s_or_b32 s22, s13, s56
	s_ashr_i32 s23, s22, 31
	s_lshl_b64 s[22:23], s[22:23], 14
	s_waitcnt vmcnt(0)
	ds_read_b128 v[230:233], v151 offset:0
	ds_read_b128 v[190:193], v152 offset:0
	ds_read_b128 v[186:189], v151 offset:2048
	ds_read_b128 v[182:185], v152 offset:2048
	ds_read_b128 v[178:181], v151 offset:4096
	ds_read_b128 v[174:177], v152 offset:4096
	ds_read_b128 v[170:173], v151 offset:6144
	ds_read_b128 v[166:169], v152 offset:6144
	ds_read_b128 v[162:165], v151 offset:8192
	ds_read_b128 v[158:161], v152 offset:8192
	ds_read_b128 v[154:157], v151 offset:10240
	ds_read_b128 v[146:149], v151 offset:12288
	ds_read_b128 v[138:141], v152 offset:12288
	ds_read_b128 v[142:145], v151 offset:14336
	ds_read_b128 v[126:129], v152 offset:14336
	ds_read_b128 v[150:153], v152 offset:10240
	s_waitcnt lgkmcnt(0)
	v_lshlrev_b32_e32 v242, 16, v230
	v_and_b32_e32 v243, 0xffff0000, v230
	v_lshlrev_b32_e32 v230, 16, v231
	v_and_b32_e32 v231, 0xffff0000, v231
	v_pk_add_f32 v[132:133], v[132:133], v[230:231]
	v_pk_add_f32 v[130:131], v[130:131], v[242:243]
	v_lshlrev_b32_e32 v244, 16, v232
	v_and_b32_e32 v245, 0xffff0000, v232
	v_mul_f32_e32 v229, v131, v131
	v_mul_f32_e32 v230, v133, v133
	v_pk_add_f32 v[134:135], v[134:135], v[244:245]
	v_fmac_f32_e32 v229, v130, v130
	v_fmac_f32_e32 v230, v132, v132
	v_add_f32_e32 v229, v229, v230
	v_mul_f32_e32 v230, v135, v135
	v_lshlrev_b32_e32 v232, 16, v233
	v_and_b32_e32 v233, 0xffff0000, v233
	v_fmac_f32_e32 v230, v134, v134
	v_cvt_pk_bf16_f32 v130, v130, v131
	v_cvt_pk_bf16_f32 v131, v132, v133
	v_cvt_pk_bf16_f32 v132, v134, v135
	v_lshl_add_u64 v[134:135], s[4:5], 0, v[224:225]
	v_pk_add_f32 v[136:137], v[136:137], v[232:233]
	v_lshl_add_u64 v[134:135], v[134:135], 0, v[222:223]
	v_cvt_pk_bf16_f32 v133, v136, v137
	v_mul_f32_e32 v231, v137, v137
	global_store_dwordx4 v[134:135], v[130:133], off sc1
	v_fmac_f32_e32 v231, v136, v136
	v_lshlrev_b32_e32 v136, 16, v192
	v_lshlrev_b32_e32 v130, 16, v190
	v_and_b32_e32 v131, 0xffff0000, v190
	v_lshlrev_b32_e32 v132, 16, v191
	v_and_b32_e32 v133, 0xffff0000, v191
	v_and_b32_e32 v137, 0xffff0000, v192
	v_lshlrev_b32_e32 v190, 16, v193
	v_and_b32_e32 v191, 0xffff0000, v193
	v_pk_add_f32 v[124:125], v[124:125], v[132:133]
	v_pk_add_f32 v[122:123], v[122:123], v[130:131]
	v_pk_add_f32 v[130:131], v[120:121], v[190:191]
	v_pk_add_f32 v[120:121], v[118:119], v[136:137]
	v_mul_f32_e32 v118, v123, v123
	v_mul_f32_e32 v119, v125, v125
	v_fmac_f32_e32 v118, v122, v122
	v_fmac_f32_e32 v119, v124, v124
	v_add_f32_e32 v118, v118, v119
	v_mul_f32_e32 v119, v121, v121
	v_mul_f32_e32 v132, v131, v131
	v_fmac_f32_e32 v119, v120, v120
	v_fmac_f32_e32 v132, v130, v130
	v_add_f32_e32 v230, v230, v231
	v_add_f32_e32 v119, v119, v132
	v_add_f32_e32 v229, v229, v230
	v_add_f32_e32 v118, v118, v119
	v_add_f32_e32 v132, v229, v118
	v_cvt_pk_bf16_f32 v118, v122, v123
	v_cvt_pk_bf16_f32 v119, v124, v125
	v_cvt_pk_bf16_f32 v120, v120, v121
	v_cvt_pk_bf16_f32 v121, v130, v131
	global_store_dwordx4 v[134:135], v[118:121], off offset:64 sc1
	s_nop 1
	v_mov_b32_e32 v118, v132
	s_nop 1
	v_permlane16_swap_b32_e32 v132, v118
	v_add_f32_e32 v118, v132, v118
	v_mov_b32_e32 v119, v118
	s_nop 1
	v_permlane32_swap_b32_e32 v118, v119
	s_and_saveexec_b64 s[24:25], s[6:7]
	s_cbranch_execz .LBB0_876
	s_add_u32 s26, s54, s22
	s_addc_u32 s27, s55, s23
	v_lshl_add_u64 v[120:121], v[194:195], 2, s[26:27]
	v_add_f32_e32 v118, v118, v119
	global_store_dword v[120:121], v118, off sc1
